# z_p epilogue (phase 4) rewritten like the phase-5 blocks: 16 PM read-backs in flight, packed silu, counted vmcnt instead of vmcnt(0) per group
# baseline (speedup 1.0000x reference)
; __device__ __forceinline__ float sigm(float x) { return __builtin_amdgcn_rcpf(1.0f + __expf(-x)); }
; __device__ __forceinline__ float siluf(float x) { return x * __builtin_amdgcn_rcpf(1.0f + __expf(-x)); }
;     __device__ __forceinline__ void operator()(const f32x4 (&acc)[2][2][4][2], const Unit& u, int wr, int wc, int fr, int fq) const {
;     ...
;         const int gl_off = ((wr * 4 + wc) * 16 * 64 + (fq * 16 + fr)) * 8;
;         const int row0 = u.pm * 256 + wr * 64 + fr, col0 = wc * 32 + 8 * fq;
;         const bf16_t* ldp = nullptr; bf16_t* stp; bool ld_lm = false, st_lm = false, act_silu = false, recip = false; int ld = 0;
;         if (wt < 16) { bf16_t* t = (bf16_t*)(ws + OFF_Q) + (size_t)(u.pm * 4 + (wt - 12)) * 65536 + gl_off; ldp = t; stp = t; ld_lm = st_lm = true; }
;         else if (wt < 20) { ldp = (const bf16_t*)(ws + OFF_Q) + (size_t)(u.pm * 4 + (wt - 16)) * 65536 + gl_off; ld_lm = true; stp = am + (wt - 16) * 256; ld = 1024; act_silu = true; }
;         else if (wt < 24) { bf16_t* t = (bf16_t*)(ws + OFF_PM) + (wt - 22) * 256; ldp = t; stp = t; ld = 512; act_silu = true; }
;         else if (wt < 28) { stp = (bf16_t*)(ws + OFF_GB) + (size_t)(u.pm * 8 + (wt - 24)) * 65536 + gl_off; st_lm = true; }
;         else { bf16_t* t = (bf16_t*)(ws + OFF_GB) + (size_t)(u.pm * 8 + (wt - 24)) * 65536 + gl_off; stp = t; st_lm = true; ldp = t - 4 * 65536; ld_lm = true; recip = true; }
; #pragma unroll
;         for (int ai = 0; ai < 2; ++ai) {
;             u32x4 old8[4][2];
;             if (ldp) {
; #pragma unroll
;                 for (int m = 0; m < 4; ++m)
; #pragma unroll
;                     for (int bj = 0; bj < 2; ++bj) old8[m][bj] = ld_lm ? *(const u32x4*)(ldp + ((ai * 4 + m) * 2 + bj) * 512)
;                                                                        : *(const u32x4*)(ldp + (size_t)(row0 + ai * 128 + m * 16) * ld + col0 + bj * 128);
;             }
; #pragma unroll
;             for (int m = 0; m < 4; ++m)
; #pragma unroll
;                 for (int bj = 0; bj < 2; ++bj) { const f32x4 a0 = acc[ai][bj][m][0], a1 = acc[ai][bj][m][1];
;                     float f[8];
; #pragma unroll
;                     for (int q = 0; q < 4; ++q) { f[q] = act_silu ? siluf(a0[q]) : sigm(a0[q]); f[4 + q] = act_silu ? siluf(a1[q]) : sigm(a1[q]); }
.Lgb3z_done:
	s_or_b64 exec, exec, s[48:49]
	s_barrier
	v_readlane_b32 s0, v254, 30
	s_lshl_b32 s0, s0, 9
	s_add_u32 s0, s70, s0
	s_addc_u32 s1, s71, 0
	s_add_u32 s2, s0, 0x93f4400
	s_addc_u32 s3, s1, 0
	v_lshl_add_u32 v160, s18, 8, v85
	v_lshl_or_b32 v162, s17, 6, v84
	v_lshl_add_u32 v164, v160, 10, v162
	v_add_u32_e32 v165, 0x4000, v164
	v_add_u32_e32 v166, 0x8000, v164
	v_add_u32_e32 v167, 0xc000, v164
	v_add_u32_e32 v168, 0x20000, v164
	v_add_u32_e32 v169, 0x24000, v164
	v_add_u32_e32 v170, 0x28000, v164
	v_add_u32_e32 v171, 0x2c000, v164
	s_mov_b32 s4, 0xbfb8aa3b
	s_mov_b32 s5, s4
	s_mov_b32 s6, 1.0
	s_mov_b32 s7, 1.0
	s_mov_b32 s1, 0xffff0000
	global_load_dwordx4 v[176:179], v164, s[2:3]
	global_load_dwordx4 v[180:183], v164, s[2:3] offset:256
	global_load_dwordx4 v[184:187], v165, s[2:3]
	global_load_dwordx4 v[188:191], v165, s[2:3] offset:256
	global_load_dwordx4 v[192:195], v166, s[2:3]
	global_load_dwordx4 v[196:199], v166, s[2:3] offset:256
	global_load_dwordx4 v[200:203], v167, s[2:3]
	global_load_dwordx4 v[204:207], v167, s[2:3] offset:256
	global_load_dwordx4 v[208:211], v168, s[2:3]
	global_load_dwordx4 v[212:215], v168, s[2:3] offset:256
	global_load_dwordx4 v[216:219], v169, s[2:3]
	global_load_dwordx4 v[220:223], v169, s[2:3] offset:256
	global_load_dwordx4 v[228:231], v170, s[2:3]
	global_load_dwordx4 v[232:235], v170, s[2:3] offset:256
	global_load_dwordx4 v[236:239], v171, s[2:3]
	global_load_dwordx4 v[240:243], v171, s[2:3] offset:256
	v_pk_mul_f32 v[244:245], v[152:153], s[4:5]
	v_pk_mul_f32 v[246:247], v[154:155], s[4:5]
	v_pk_mul_f32 v[248:249], v[156:157], s[4:5]
	v_pk_mul_f32 v[250:251], v[158:159], s[4:5]
	v_exp_f32_e32 v244, v244
	v_exp_f32_e32 v245, v245
	v_exp_f32_e32 v246, v246
	v_exp_f32_e32 v247, v247
	v_exp_f32_e32 v248, v248
	v_exp_f32_e32 v249, v249
	v_exp_f32_e32 v250, v250
	v_exp_f32_e32 v251, v251
	v_pk_add_f32 v[244:245], v[244:245], s[6:7]
	v_pk_add_f32 v[246:247], v[246:247], s[6:7]
	v_pk_add_f32 v[248:249], v[248:249], s[6:7]
	v_pk_add_f32 v[250:251], v[250:251], s[6:7]
	v_rcp_f32_e32 v244, v244
	v_rcp_f32_e32 v245, v245
	v_rcp_f32_e32 v246, v246
	v_rcp_f32_e32 v247, v247
	v_rcp_f32_e32 v248, v248
	v_rcp_f32_e32 v249, v249
	v_rcp_f32_e32 v250, v250
	v_rcp_f32_e32 v251, v251
	v_pk_mul_f32 v[152:153], v[152:153], v[244:245]
	v_pk_mul_f32 v[154:155], v[154:155], v[246:247]
	v_pk_mul_f32 v[156:157], v[156:157], v[248:249]
	v_pk_mul_f32 v[158:159], v[158:159], v[250:251]
	v_pk_mul_f32 v[244:245], v[144:145], s[4:5]
	v_pk_mul_f32 v[246:247], v[146:147], s[4:5]
	v_pk_mul_f32 v[248:249], v[148:149], s[4:5]
	v_pk_mul_f32 v[250:251], v[150:151], s[4:5]
	v_exp_f32_e32 v244, v244
	v_exp_f32_e32 v245, v245
	v_exp_f32_e32 v246, v246
	v_exp_f32_e32 v247, v247
	v_exp_f32_e32 v248, v248
	v_exp_f32_e32 v249, v249
	v_exp_f32_e32 v250, v250
	v_exp_f32_e32 v251, v251
	v_pk_add_f32 v[244:245], v[244:245], s[6:7]
	v_pk_add_f32 v[246:247], v[246:247], s[6:7]
	v_pk_add_f32 v[248:249], v[248:249], s[6:7]
	v_pk_add_f32 v[250:251], v[250:251], s[6:7]
	v_rcp_f32_e32 v244, v244
	v_rcp_f32_e32 v245, v245
	v_rcp_f32_e32 v246, v246
	v_rcp_f32_e32 v247, v247
	v_rcp_f32_e32 v248, v248
	v_rcp_f32_e32 v249, v249
	v_rcp_f32_e32 v250, v250
	v_rcp_f32_e32 v251, v251
	v_pk_mul_f32 v[144:145], v[144:145], v[244:245]
	v_pk_mul_f32 v[146:147], v[146:147], v[246:247]
	v_pk_mul_f32 v[148:149], v[148:149], v[248:249]
	v_pk_mul_f32 v[150:151], v[150:151], v[250:251]
	v_pk_mul_f32 v[244:245], v[136:137], s[4:5]
	v_pk_mul_f32 v[246:247], v[138:139], s[4:5]
	v_pk_mul_f32 v[248:249], v[140:141], s[4:5]
	v_pk_mul_f32 v[250:251], v[142:143], s[4:5]
	v_exp_f32_e32 v244, v244
	v_exp_f32_e32 v245, v245
	v_exp_f32_e32 v246, v246
	v_exp_f32_e32 v247, v247
	v_exp_f32_e32 v248, v248
	v_exp_f32_e32 v249, v249
	v_exp_f32_e32 v250, v250
	v_exp_f32_e32 v251, v251
	v_pk_add_f32 v[244:245], v[244:245], s[6:7]
	v_pk_add_f32 v[246:247], v[246:247], s[6:7]
	v_pk_add_f32 v[248:249], v[248:249], s[6:7]
	v_pk_add_f32 v[250:251], v[250:251], s[6:7]
	v_rcp_f32_e32 v244, v244
	v_rcp_f32_e32 v245, v245
	v_rcp_f32_e32 v246, v246
	v_rcp_f32_e32 v247, v247
	v_rcp_f32_e32 v248, v248
	v_rcp_f32_e32 v249, v249
	v_rcp_f32_e32 v250, v250
	v_rcp_f32_e32 v251, v251
	v_pk_mul_f32 v[136:137], v[136:137], v[244:245]
	v_pk_mul_f32 v[138:139], v[138:139], v[246:247]
	v_pk_mul_f32 v[140:141], v[140:141], v[248:249]
	v_pk_mul_f32 v[142:143], v[142:143], v[250:251]
	v_pk_mul_f32 v[244:245], v[128:129], s[4:5]
	v_pk_mul_f32 v[246:247], v[130:131], s[4:5]
	v_pk_mul_f32 v[248:249], v[132:133], s[4:5]
	v_pk_mul_f32 v[250:251], v[134:135], s[4:5]
	v_exp_f32_e32 v244, v244
	v_exp_f32_e32 v245, v245
	v_exp_f32_e32 v246, v246
	v_exp_f32_e32 v247, v247
	v_exp_f32_e32 v248, v248
	v_exp_f32_e32 v249, v249
	v_exp_f32_e32 v250, v250
	v_exp_f32_e32 v251, v251
	v_pk_add_f32 v[244:245], v[244:245], s[6:7]
	v_pk_add_f32 v[246:247], v[246:247], s[6:7]
	v_pk_add_f32 v[248:249], v[248:249], s[6:7]
	v_pk_add_f32 v[250:251], v[250:251], s[6:7]
	v_rcp_f32_e32 v244, v244
	v_rcp_f32_e32 v245, v245
	v_rcp_f32_e32 v246, v246
	v_rcp_f32_e32 v247, v247
	v_rcp_f32_e32 v248, v248
	v_rcp_f32_e32 v249, v249
	v_rcp_f32_e32 v250, v250
	v_rcp_f32_e32 v251, v251
	v_pk_mul_f32 v[128:129], v[128:129], v[244:245]
	v_pk_mul_f32 v[130:131], v[130:131], v[246:247]
	v_pk_mul_f32 v[132:133], v[132:133], v[248:249]
	v_pk_mul_f32 v[134:135], v[134:135], v[250:251]
	v_pk_mul_f32 v[244:245], v[116:117], s[4:5]
	v_pk_mul_f32 v[246:247], v[118:119], s[4:5]
	v_pk_mul_f32 v[248:249], v[120:121], s[4:5]
	v_pk_mul_f32 v[250:251], v[122:123], s[4:5]
	v_exp_f32_e32 v244, v244
	v_exp_f32_e32 v245, v245
	v_exp_f32_e32 v246, v246
; __device__ __forceinline__ float sigm(float x) { return __builtin_amdgcn_rcpf(1.0f + __expf(-x)); }
; __device__ __forceinline__ float siluf(float x) { return x * __builtin_amdgcn_rcpf(1.0f + __expf(-x)); }
;     __device__ __forceinline__ void operator()(const f32x4 (&acc)[2][2][4][2], const Unit& u, int wr, int wc, int fr, int fq) const {
;     ...
;                 for (int bj = 0; bj < 2; ++bj) { const f32x4 a0 = acc[ai][bj][m][0], a1 = acc[ai][bj][m][1];
;                     float f[8];
; #pragma unroll
;                     for (int q = 0; q < 4; ++q) { f[q] = act_silu ? siluf(a0[q]) : sigm(a0[q]); f[4 + q] = act_silu ? siluf(a1[q]) : sigm(a1[q]); }
	v_exp_f32_e32 v247, v247
	v_exp_f32_e32 v248, v248
	v_exp_f32_e32 v249, v249
	v_exp_f32_e32 v250, v250
	v_exp_f32_e32 v251, v251
	v_pk_add_f32 v[244:245], v[244:245], s[6:7]
	v_pk_add_f32 v[246:247], v[246:247], s[6:7]
	v_pk_add_f32 v[248:249], v[248:249], s[6:7]
	v_pk_add_f32 v[250:251], v[250:251], s[6:7]
	v_rcp_f32_e32 v244, v244
	v_rcp_f32_e32 v245, v245
	v_rcp_f32_e32 v246, v246
	v_rcp_f32_e32 v247, v247
	v_rcp_f32_e32 v248, v248
	v_rcp_f32_e32 v249, v249
	v_rcp_f32_e32 v250, v250
	v_rcp_f32_e32 v251, v251
	v_pk_mul_f32 v[116:117], v[116:117], v[244:245]
	v_pk_mul_f32 v[118:119], v[118:119], v[246:247]
	v_pk_mul_f32 v[120:121], v[120:121], v[248:249]
	v_pk_mul_f32 v[122:123], v[122:123], v[250:251]
	v_pk_mul_f32 v[244:245], v[104:105], s[4:5]
	v_pk_mul_f32 v[246:247], v[106:107], s[4:5]
	v_pk_mul_f32 v[248:249], v[108:109], s[4:5]
	v_pk_mul_f32 v[250:251], v[110:111], s[4:5]
	v_exp_f32_e32 v244, v244
	v_exp_f32_e32 v245, v245
	v_exp_f32_e32 v246, v246
	v_exp_f32_e32 v247, v247
	v_exp_f32_e32 v248, v248
	v_exp_f32_e32 v249, v249
	v_exp_f32_e32 v250, v250
	v_exp_f32_e32 v251, v251
	v_pk_add_f32 v[244:245], v[244:245], s[6:7]
	v_pk_add_f32 v[246:247], v[246:247], s[6:7]
	v_pk_add_f32 v[248:249], v[248:249], s[6:7]
	v_pk_add_f32 v[250:251], v[250:251], s[6:7]
	v_rcp_f32_e32 v244, v244
	v_rcp_f32_e32 v245, v245
	v_rcp_f32_e32 v246, v246
	v_rcp_f32_e32 v247, v247
	v_rcp_f32_e32 v248, v248
	v_rcp_f32_e32 v249, v249
	v_rcp_f32_e32 v250, v250
	v_rcp_f32_e32 v251, v251
	v_pk_mul_f32 v[104:105], v[104:105], v[244:245]
	v_pk_mul_f32 v[106:107], v[106:107], v[246:247]
	v_pk_mul_f32 v[108:109], v[108:109], v[248:249]
	v_pk_mul_f32 v[110:111], v[110:111], v[250:251]
	v_pk_mul_f32 v[244:245], v[92:93], s[4:5]
	v_pk_mul_f32 v[246:247], v[94:95], s[4:5]
	v_pk_mul_f32 v[248:249], v[96:97], s[4:5]
	v_pk_mul_f32 v[250:251], v[98:99], s[4:5]
	v_exp_f32_e32 v244, v244
	v_exp_f32_e32 v245, v245
	v_exp_f32_e32 v246, v246
	v_exp_f32_e32 v247, v247
	v_exp_f32_e32 v248, v248
	v_exp_f32_e32 v249, v249
	v_exp_f32_e32 v250, v250
	v_exp_f32_e32 v251, v251
	v_pk_add_f32 v[244:245], v[244:245], s[6:7]
	v_pk_add_f32 v[246:247], v[246:247], s[6:7]
	v_pk_add_f32 v[248:249], v[248:249], s[6:7]
	v_pk_add_f32 v[250:251], v[250:251], s[6:7]
	v_rcp_f32_e32 v244, v244
	v_rcp_f32_e32 v245, v245
	v_rcp_f32_e32 v246, v246
	v_rcp_f32_e32 v247, v247
	v_rcp_f32_e32 v248, v248
	v_rcp_f32_e32 v249, v249
	v_rcp_f32_e32 v250, v250
	v_rcp_f32_e32 v251, v251
	v_pk_mul_f32 v[92:93], v[92:93], v[244:245]
	v_pk_mul_f32 v[94:95], v[94:95], v[246:247]
	v_pk_mul_f32 v[96:97], v[96:97], v[248:249]
	v_pk_mul_f32 v[98:99], v[98:99], v[250:251]
	v_pk_mul_f32 v[244:245], v[76:77], s[4:5]
	v_pk_mul_f32 v[246:247], v[78:79], s[4:5]
	v_pk_mul_f32 v[248:249], v[80:81], s[4:5]
	v_pk_mul_f32 v[250:251], v[82:83], s[4:5]
	v_exp_f32_e32 v244, v244
	v_exp_f32_e32 v245, v245
	v_exp_f32_e32 v246, v246
	v_exp_f32_e32 v247, v247
	v_exp_f32_e32 v248, v248
	v_exp_f32_e32 v249, v249
	v_exp_f32_e32 v250, v250
	v_exp_f32_e32 v251, v251
	v_pk_add_f32 v[244:245], v[244:245], s[6:7]
	v_pk_add_f32 v[246:247], v[246:247], s[6:7]
	v_pk_add_f32 v[248:249], v[248:249], s[6:7]
	v_pk_add_f32 v[250:251], v[250:251], s[6:7]
	v_rcp_f32_e32 v244, v244
	v_rcp_f32_e32 v245, v245
	v_rcp_f32_e32 v246, v246
	v_rcp_f32_e32 v247, v247
	v_rcp_f32_e32 v248, v248
	v_rcp_f32_e32 v249, v249
	v_rcp_f32_e32 v250, v250
	v_rcp_f32_e32 v251, v251
	v_pk_mul_f32 v[76:77], v[76:77], v[244:245]
	v_pk_mul_f32 v[78:79], v[78:79], v[246:247]
	v_pk_mul_f32 v[80:81], v[80:81], v[248:249]
	v_pk_mul_f32 v[82:83], v[82:83], v[250:251]
	v_pk_mul_f32 v[244:245], v[64:65], s[4:5]
	v_pk_mul_f32 v[246:247], v[66:67], s[4:5]
	v_pk_mul_f32 v[248:249], v[68:69], s[4:5]
	v_pk_mul_f32 v[250:251], v[70:71], s[4:5]
	v_exp_f32_e32 v244, v244
	v_exp_f32_e32 v245, v245
	v_exp_f32_e32 v246, v246
	v_exp_f32_e32 v247, v247
	v_exp_f32_e32 v248, v248
	v_exp_f32_e32 v249, v249
	v_exp_f32_e32 v250, v250
	v_exp_f32_e32 v251, v251
	v_pk_add_f32 v[244:245], v[244:245], s[6:7]
	v_pk_add_f32 v[246:247], v[246:247], s[6:7]
	v_pk_add_f32 v[248:249], v[248:249], s[6:7]
	v_pk_add_f32 v[250:251], v[250:251], s[6:7]
	v_rcp_f32_e32 v244, v244
	v_rcp_f32_e32 v245, v245
	v_rcp_f32_e32 v246, v246
	v_rcp_f32_e32 v247, v247
	v_rcp_f32_e32 v248, v248
	v_rcp_f32_e32 v249, v249
	v_rcp_f32_e32 v250, v250
	v_rcp_f32_e32 v251, v251
	v_pk_mul_f32 v[64:65], v[64:65], v[244:245]
	v_pk_mul_f32 v[66:67], v[66:67], v[246:247]
	v_pk_mul_f32 v[68:69], v[68:69], v[248:249]
	v_pk_mul_f32 v[70:71], v[70:71], v[250:251]
	v_pk_mul_f32 v[244:245], v[52:53], s[4:5]
	v_pk_mul_f32 v[246:247], v[54:55], s[4:5]
	v_pk_mul_f32 v[248:249], v[56:57], s[4:5]
	v_pk_mul_f32 v[250:251], v[58:59], s[4:5]
	v_exp_f32_e32 v244, v244
	v_exp_f32_e32 v245, v245
	v_exp_f32_e32 v246, v246
	v_exp_f32_e32 v247, v247
	v_exp_f32_e32 v248, v248
	v_exp_f32_e32 v249, v249
	v_exp_f32_e32 v250, v250
	v_exp_f32_e32 v251, v251
	v_pk_add_f32 v[244:245], v[244:245], s[6:7]
	v_pk_add_f32 v[246:247], v[246:247], s[6:7]
	v_pk_add_f32 v[248:249], v[248:249], s[6:7]
	v_pk_add_f32 v[250:251], v[250:251], s[6:7]
	v_rcp_f32_e32 v244, v244
	v_rcp_f32_e32 v245, v245
	v_rcp_f32_e32 v246, v246
	v_rcp_f32_e32 v247, v247
	v_rcp_f32_e32 v248, v248
	v_rcp_f32_e32 v249, v249
	v_rcp_f32_e32 v250, v250
	v_rcp_f32_e32 v251, v251
	v_pk_mul_f32 v[52:53], v[52:53], v[244:245]
	v_pk_mul_f32 v[54:55], v[54:55], v[246:247]
	v_pk_mul_f32 v[56:57], v[56:57], v[248:249]
	v_pk_mul_f32 v[58:59], v[58:59], v[250:251]
	v_pk_mul_f32 v[244:245], v[40:41], s[4:5]
	v_pk_mul_f32 v[246:247], v[42:43], s[4:5]
	v_pk_mul_f32 v[248:249], v[44:45], s[4:5]
	v_pk_mul_f32 v[250:251], v[46:47], s[4:5]
; __device__ __forceinline__ float sigm(float x) { return __builtin_amdgcn_rcpf(1.0f + __expf(-x)); }
; __device__ __forceinline__ float siluf(float x) { return x * __builtin_amdgcn_rcpf(1.0f + __expf(-x)); }
;     __device__ __forceinline__ void operator()(const f32x4 (&acc)[2][2][4][2], const Unit& u, int wr, int wc, int fr, int fq) const {
;     ...
;                 for (int bj = 0; bj < 2; ++bj) { const f32x4 a0 = acc[ai][bj][m][0], a1 = acc[ai][bj][m][1];
;                     float f[8];
; #pragma unroll
;                     for (int q = 0; q < 4; ++q) { f[q] = act_silu ? siluf(a0[q]) : sigm(a0[q]); f[4 + q] = act_silu ? siluf(a1[q]) : sigm(a1[q]); }
	v_exp_f32_e32 v244, v244
	v_exp_f32_e32 v245, v245
	v_exp_f32_e32 v246, v246
	v_exp_f32_e32 v247, v247
	v_exp_f32_e32 v248, v248
	v_exp_f32_e32 v249, v249
	v_exp_f32_e32 v250, v250
	v_exp_f32_e32 v251, v251
	v_pk_add_f32 v[244:245], v[244:245], s[6:7]
	v_pk_add_f32 v[246:247], v[246:247], s[6:7]
	v_pk_add_f32 v[248:249], v[248:249], s[6:7]
	v_pk_add_f32 v[250:251], v[250:251], s[6:7]
	v_rcp_f32_e32 v244, v244
	v_rcp_f32_e32 v245, v245
	v_rcp_f32_e32 v246, v246
	v_rcp_f32_e32 v247, v247
	v_rcp_f32_e32 v248, v248
	v_rcp_f32_e32 v249, v249
	v_rcp_f32_e32 v250, v250
	v_rcp_f32_e32 v251, v251
	v_pk_mul_f32 v[40:41], v[40:41], v[244:245]
	v_pk_mul_f32 v[42:43], v[42:43], v[246:247]
	v_pk_mul_f32 v[44:45], v[44:45], v[248:249]
	v_pk_mul_f32 v[46:47], v[46:47], v[250:251]
	v_pk_mul_f32 v[244:245], v[32:33], s[4:5]
	v_pk_mul_f32 v[246:247], v[34:35], s[4:5]
	v_pk_mul_f32 v[248:249], v[36:37], s[4:5]
	v_pk_mul_f32 v[250:251], v[38:39], s[4:5]
	v_exp_f32_e32 v244, v244
	v_exp_f32_e32 v245, v245
	v_exp_f32_e32 v246, v246
	v_exp_f32_e32 v247, v247
	v_exp_f32_e32 v248, v248
	v_exp_f32_e32 v249, v249
	v_exp_f32_e32 v250, v250
	v_exp_f32_e32 v251, v251
	v_pk_add_f32 v[244:245], v[244:245], s[6:7]
	v_pk_add_f32 v[246:247], v[246:247], s[6:7]
	v_pk_add_f32 v[248:249], v[248:249], s[6:7]
	v_pk_add_f32 v[250:251], v[250:251], s[6:7]
	v_rcp_f32_e32 v244, v244
	v_rcp_f32_e32 v245, v245
	v_rcp_f32_e32 v246, v246
	v_rcp_f32_e32 v247, v247
	v_rcp_f32_e32 v248, v248
	v_rcp_f32_e32 v249, v249
	v_rcp_f32_e32 v250, v250
	v_rcp_f32_e32 v251, v251
	v_pk_mul_f32 v[32:33], v[32:33], v[244:245]
	v_pk_mul_f32 v[34:35], v[34:35], v[246:247]
	v_pk_mul_f32 v[36:37], v[36:37], v[248:249]
	v_pk_mul_f32 v[38:39], v[38:39], v[250:251]
	v_pk_mul_f32 v[244:245], v[24:25], s[4:5]
	v_pk_mul_f32 v[246:247], v[26:27], s[4:5]
	v_pk_mul_f32 v[248:249], v[28:29], s[4:5]
	v_pk_mul_f32 v[250:251], v[30:31], s[4:5]
	v_exp_f32_e32 v244, v244
	v_exp_f32_e32 v245, v245
	v_exp_f32_e32 v246, v246
	v_exp_f32_e32 v247, v247
	v_exp_f32_e32 v248, v248
	v_exp_f32_e32 v249, v249
	v_exp_f32_e32 v250, v250
	v_exp_f32_e32 v251, v251
	v_pk_add_f32 v[244:245], v[244:245], s[6:7]
	v_pk_add_f32 v[246:247], v[246:247], s[6:7]
	v_pk_add_f32 v[248:249], v[248:249], s[6:7]
	v_pk_add_f32 v[250:251], v[250:251], s[6:7]
	v_rcp_f32_e32 v244, v244
	v_rcp_f32_e32 v245, v245
	v_rcp_f32_e32 v246, v246
	v_rcp_f32_e32 v247, v247
	v_rcp_f32_e32 v248, v248
	v_rcp_f32_e32 v249, v249
	v_rcp_f32_e32 v250, v250
	v_rcp_f32_e32 v251, v251
	v_pk_mul_f32 v[24:25], v[24:25], v[244:245]
	v_pk_mul_f32 v[26:27], v[26:27], v[246:247]
	v_pk_mul_f32 v[28:29], v[28:29], v[248:249]
	v_pk_mul_f32 v[30:31], v[30:31], v[250:251]
	v_pk_mul_f32 v[244:245], v[16:17], s[4:5]
	v_pk_mul_f32 v[246:247], v[18:19], s[4:5]
	v_pk_mul_f32 v[248:249], v[20:21], s[4:5]
	v_pk_mul_f32 v[250:251], v[22:23], s[4:5]
	v_exp_f32_e32 v244, v244
	v_exp_f32_e32 v245, v245
	v_exp_f32_e32 v246, v246
	v_exp_f32_e32 v247, v247
	v_exp_f32_e32 v248, v248
	v_exp_f32_e32 v249, v249
	v_exp_f32_e32 v250, v250
	v_exp_f32_e32 v251, v251
	v_pk_add_f32 v[244:245], v[244:245], s[6:7]
	v_pk_add_f32 v[246:247], v[246:247], s[6:7]
	v_pk_add_f32 v[248:249], v[248:249], s[6:7]
	v_pk_add_f32 v[250:251], v[250:251], s[6:7]
	v_rcp_f32_e32 v244, v244
	v_rcp_f32_e32 v245, v245
	v_rcp_f32_e32 v246, v246
	v_rcp_f32_e32 v247, v247
	v_rcp_f32_e32 v248, v248
	v_rcp_f32_e32 v249, v249
	v_rcp_f32_e32 v250, v250
	v_rcp_f32_e32 v251, v251
	v_pk_mul_f32 v[16:17], v[16:17], v[244:245]
	v_pk_mul_f32 v[18:19], v[18:19], v[246:247]
	v_pk_mul_f32 v[20:21], v[20:21], v[248:249]
	v_pk_mul_f32 v[22:23], v[22:23], v[250:251]
	v_pk_mul_f32 v[244:245], v[8:9], s[4:5]
	v_pk_mul_f32 v[246:247], v[10:11], s[4:5]
	v_pk_mul_f32 v[248:249], v[12:13], s[4:5]
	v_pk_mul_f32 v[250:251], v[14:15], s[4:5]
	v_exp_f32_e32 v244, v244
	v_exp_f32_e32 v245, v245
	v_exp_f32_e32 v246, v246
	v_exp_f32_e32 v247, v247
	v_exp_f32_e32 v248, v248
	v_exp_f32_e32 v249, v249
	v_exp_f32_e32 v250, v250
	v_exp_f32_e32 v251, v251
	v_pk_add_f32 v[244:245], v[244:245], s[6:7]
	v_pk_add_f32 v[246:247], v[246:247], s[6:7]
	v_pk_add_f32 v[248:249], v[248:249], s[6:7]
	v_pk_add_f32 v[250:251], v[250:251], s[6:7]
	v_rcp_f32_e32 v244, v244
	v_rcp_f32_e32 v245, v245
	v_rcp_f32_e32 v246, v246
	v_rcp_f32_e32 v247, v247
	v_rcp_f32_e32 v248, v248
	v_rcp_f32_e32 v249, v249
	v_rcp_f32_e32 v250, v250
	v_rcp_f32_e32 v251, v251
	v_pk_mul_f32 v[8:9], v[8:9], v[244:245]
	v_pk_mul_f32 v[10:11], v[10:11], v[246:247]
	v_pk_mul_f32 v[12:13], v[12:13], v[248:249]
	v_pk_mul_f32 v[14:15], v[14:15], v[250:251]
	v_pk_mul_f32 v[244:245], v[0:1], s[4:5]
	v_pk_mul_f32 v[246:247], v[2:3], s[4:5]
	v_pk_mul_f32 v[248:249], v[4:5], s[4:5]
	v_pk_mul_f32 v[250:251], v[6:7], s[4:5]
	v_exp_f32_e32 v244, v244
	v_exp_f32_e32 v245, v245
	v_exp_f32_e32 v246, v246
	v_exp_f32_e32 v247, v247
	v_exp_f32_e32 v248, v248
	v_exp_f32_e32 v249, v249
	v_exp_f32_e32 v250, v250
	v_exp_f32_e32 v251, v251
	v_pk_add_f32 v[244:245], v[244:245], s[6:7]
	v_pk_add_f32 v[246:247], v[246:247], s[6:7]
	v_pk_add_f32 v[248:249], v[248:249], s[6:7]
	v_pk_add_f32 v[250:251], v[250:251], s[6:7]
	v_rcp_f32_e32 v244, v244
	v_rcp_f32_e32 v245, v245
	v_rcp_f32_e32 v246, v246
	v_rcp_f32_e32 v247, v247
	v_rcp_f32_e32 v248, v248
	v_rcp_f32_e32 v249, v249
	v_rcp_f32_e32 v250, v250
	v_rcp_f32_e32 v251, v251
	v_pk_mul_f32 v[0:1], v[0:1], v[244:245]
	v_pk_mul_f32 v[2:3], v[2:3], v[246:247]
	v_pk_mul_f32 v[4:5], v[4:5], v[248:249]
	v_pk_mul_f32 v[6:7], v[6:7], v[250:251]
	s_waitcnt vmcnt(15)
; __device__ __forceinline__ float bf_lo(unsigned w) { return __uint_as_float(w << 16); }
; __device__ __forceinline__ float bf_hi(unsigned w) { return __uint_as_float(w & 0xffff0000u); }
; __device__ __forceinline__ unsigned cvt_pk_bf16(float lo, float hi) { unsigned r; asm volatile("v_cvt_pk_bf16_f32 %0, %1, %2" : "=v"(r) : "v"(lo), "v"(hi)); return r; }
;     __device__ __forceinline__ void operator()(const f32x4 (&acc)[2][2][4][2], const Unit& u, int wr, int wc, int fr, int fq) const {
;     ...
;                     if (ldp) { const u32x4 o = old8[m][bj];
;                         if (recip) { f[0] *= __builtin_amdgcn_rcpf(bf_lo(o.x)); f[1] *= __builtin_amdgcn_rcpf(bf_hi(o.x)); f[2] *= __builtin_amdgcn_rcpf(bf_lo(o.y)); f[3] *= __builtin_amdgcn_rcpf(bf_hi(o.y));
;                             f[4] *= __builtin_amdgcn_rcpf(bf_lo(o.z)); f[5] *= __builtin_amdgcn_rcpf(bf_hi(o.z)); f[6] *= __builtin_amdgcn_rcpf(bf_lo(o.w)); f[7] *= __builtin_amdgcn_rcpf(bf_hi(o.w)); }
;                         else { f[0] *= bf_lo(o.x); f[1] *= bf_hi(o.x); f[2] *= bf_lo(o.y); f[3] *= bf_hi(o.y); f[4] *= bf_lo(o.z); f[5] *= bf_hi(o.z); f[6] *= bf_lo(o.w); f[7] *= bf_hi(o.w); } }
;                     u32x4 w; w.x = cvt_pk_bf16(f[0], f[1]); w.y = cvt_pk_bf16(f[2], f[3]); w.z = cvt_pk_bf16(f[4], f[5]); w.w = cvt_pk_bf16(f[6], f[7]);
;                     if (st_lm) { if (recip) __builtin_nontemporal_store(w, (u32x4*)(stp + ((ai * 4 + m) * 2 + bj) * 512)); else *(u32x4*)(stp + ((ai * 4 + m) * 2 + bj) * 512) = w; }
;                     else *(u32x4*)(stp + (size_t)(row0 + ai * 128 + m * 16) * ld + col0 + bj * 128) = w; } }
	v_lshlrev_b32_e32 v244, 16, v176
	v_and_b32_e32 v245, s1, v176
	v_lshlrev_b32_e32 v246, 16, v177
	v_and_b32_e32 v247, s1, v177
	v_lshlrev_b32_e32 v248, 16, v178
	v_and_b32_e32 v249, s1, v178
	v_lshlrev_b32_e32 v250, 16, v179
	v_and_b32_e32 v251, s1, v179
	v_pk_mul_f32 v[156:157], v[156:157], v[244:245]
	v_pk_mul_f32 v[158:159], v[158:159], v[246:247]
	v_pk_mul_f32 v[152:153], v[152:153], v[248:249]
	v_pk_mul_f32 v[154:155], v[154:155], v[250:251]
	v_cvt_pk_bf16_f32 v176, v156, v157
	v_cvt_pk_bf16_f32 v177, v158, v159
	v_cvt_pk_bf16_f32 v178, v152, v153
	v_cvt_pk_bf16_f32 v179, v154, v155
	global_store_dwordx4 v164, v[176:179], s[2:3]
	s_waitcnt vmcnt(15)
	v_lshlrev_b32_e32 v244, 16, v180
	v_and_b32_e32 v245, s1, v180
	v_lshlrev_b32_e32 v246, 16, v181
	v_and_b32_e32 v247, s1, v181
	v_lshlrev_b32_e32 v248, 16, v182
	v_and_b32_e32 v249, s1, v182
	v_lshlrev_b32_e32 v250, 16, v183
	v_and_b32_e32 v251, s1, v183
	v_pk_mul_f32 v[148:149], v[148:149], v[244:245]
	v_pk_mul_f32 v[150:151], v[150:151], v[246:247]
	v_pk_mul_f32 v[144:145], v[144:145], v[248:249]
	v_pk_mul_f32 v[146:147], v[146:147], v[250:251]
	v_cvt_pk_bf16_f32 v180, v148, v149
	v_cvt_pk_bf16_f32 v181, v150, v151
	v_cvt_pk_bf16_f32 v182, v144, v145
	v_cvt_pk_bf16_f32 v183, v146, v147
	global_store_dwordx4 v164, v[180:183], s[2:3] offset:256
	s_waitcnt vmcnt(15)
	v_lshlrev_b32_e32 v244, 16, v184
	v_and_b32_e32 v245, s1, v184
	v_lshlrev_b32_e32 v246, 16, v185
	v_and_b32_e32 v247, s1, v185
	v_lshlrev_b32_e32 v248, 16, v186
	v_and_b32_e32 v249, s1, v186
	v_lshlrev_b32_e32 v250, 16, v187
	v_and_b32_e32 v251, s1, v187
	v_pk_mul_f32 v[140:141], v[140:141], v[244:245]
	v_pk_mul_f32 v[142:143], v[142:143], v[246:247]
	v_pk_mul_f32 v[136:137], v[136:137], v[248:249]
	v_pk_mul_f32 v[138:139], v[138:139], v[250:251]
	v_cvt_pk_bf16_f32 v184, v140, v141
	v_cvt_pk_bf16_f32 v185, v142, v143
	v_cvt_pk_bf16_f32 v186, v136, v137
	v_cvt_pk_bf16_f32 v187, v138, v139
	global_store_dwordx4 v165, v[184:187], s[2:3]
	s_waitcnt vmcnt(15)
	v_lshlrev_b32_e32 v244, 16, v188
	v_and_b32_e32 v245, s1, v188
	v_lshlrev_b32_e32 v246, 16, v189
	v_and_b32_e32 v247, s1, v189
	v_lshlrev_b32_e32 v248, 16, v190
	v_and_b32_e32 v249, s1, v190
	v_lshlrev_b32_e32 v250, 16, v191
	v_and_b32_e32 v251, s1, v191
	v_pk_mul_f32 v[132:133], v[132:133], v[244:245]
	v_pk_mul_f32 v[134:135], v[134:135], v[246:247]
	v_pk_mul_f32 v[128:129], v[128:129], v[248:249]
	v_pk_mul_f32 v[130:131], v[130:131], v[250:251]
	v_cvt_pk_bf16_f32 v188, v132, v133
	v_cvt_pk_bf16_f32 v189, v134, v135
	v_cvt_pk_bf16_f32 v190, v128, v129
	v_cvt_pk_bf16_f32 v191, v130, v131
	global_store_dwordx4 v165, v[188:191], s[2:3] offset:256
	s_waitcnt vmcnt(15)
	v_lshlrev_b32_e32 v244, 16, v192
	v_and_b32_e32 v245, s1, v192
	v_lshlrev_b32_e32 v246, 16, v193
	v_and_b32_e32 v247, s1, v193
	v_lshlrev_b32_e32 v248, 16, v194
	v_and_b32_e32 v249, s1, v194
	v_lshlrev_b32_e32 v250, 16, v195
	v_and_b32_e32 v251, s1, v195
	v_pk_mul_f32 v[120:121], v[120:121], v[244:245]
	v_pk_mul_f32 v[122:123], v[122:123], v[246:247]
	v_pk_mul_f32 v[116:117], v[116:117], v[248:249]
	v_pk_mul_f32 v[118:119], v[118:119], v[250:251]
	v_cvt_pk_bf16_f32 v192, v120, v121
	v_cvt_pk_bf16_f32 v193, v122, v123
	v_cvt_pk_bf16_f32 v194, v116, v117
	v_cvt_pk_bf16_f32 v195, v118, v119
	global_store_dwordx4 v166, v[192:195], s[2:3]
	s_waitcnt vmcnt(15)
	v_lshlrev_b32_e32 v244, 16, v196
	v_and_b32_e32 v245, s1, v196
	v_lshlrev_b32_e32 v246, 16, v197
	v_and_b32_e32 v247, s1, v197
	v_lshlrev_b32_e32 v248, 16, v198
	v_and_b32_e32 v249, s1, v198
	v_lshlrev_b32_e32 v250, 16, v199
	v_and_b32_e32 v251, s1, v199
	v_pk_mul_f32 v[108:109], v[108:109], v[244:245]
	v_pk_mul_f32 v[110:111], v[110:111], v[246:247]
	v_pk_mul_f32 v[104:105], v[104:105], v[248:249]
	v_pk_mul_f32 v[106:107], v[106:107], v[250:251]
	v_cvt_pk_bf16_f32 v196, v108, v109
	v_cvt_pk_bf16_f32 v197, v110, v111
	v_cvt_pk_bf16_f32 v198, v104, v105
	v_cvt_pk_bf16_f32 v199, v106, v107
	global_store_dwordx4 v166, v[196:199], s[2:3] offset:256
	s_waitcnt vmcnt(15)
	v_lshlrev_b32_e32 v244, 16, v200
	v_and_b32_e32 v245, s1, v200
	v_lshlrev_b32_e32 v246, 16, v201
	v_and_b32_e32 v247, s1, v201
	v_lshlrev_b32_e32 v248, 16, v202
	v_and_b32_e32 v249, s1, v202
	v_lshlrev_b32_e32 v250, 16, v203
	v_and_b32_e32 v251, s1, v203
	v_pk_mul_f32 v[96:97], v[96:97], v[244:245]
	v_pk_mul_f32 v[98:99], v[98:99], v[246:247]
	v_pk_mul_f32 v[92:93], v[92:93], v[248:249]
	v_pk_mul_f32 v[94:95], v[94:95], v[250:251]
	v_cvt_pk_bf16_f32 v200, v96, v97
	v_cvt_pk_bf16_f32 v201, v98, v99
	v_cvt_pk_bf16_f32 v202, v92, v93
	v_cvt_pk_bf16_f32 v203, v94, v95
	global_store_dwordx4 v167, v[200:203], s[2:3]
	s_waitcnt vmcnt(15)
	v_lshlrev_b32_e32 v244, 16, v204
	v_and_b32_e32 v245, s1, v204
	v_lshlrev_b32_e32 v246, 16, v205
	v_and_b32_e32 v247, s1, v205
	v_lshlrev_b32_e32 v248, 16, v206
	v_and_b32_e32 v249, s1, v206
	v_lshlrev_b32_e32 v250, 16, v207
	v_and_b32_e32 v251, s1, v207
	v_pk_mul_f32 v[80:81], v[80:81], v[244:245]
	v_pk_mul_f32 v[82:83], v[82:83], v[246:247]
	v_pk_mul_f32 v[76:77], v[76:77], v[248:249]
	v_pk_mul_f32 v[78:79], v[78:79], v[250:251]
	v_cvt_pk_bf16_f32 v204, v80, v81
	v_cvt_pk_bf16_f32 v205, v82, v83
	v_cvt_pk_bf16_f32 v206, v76, v77
	v_cvt_pk_bf16_f32 v207, v78, v79
	global_store_dwordx4 v167, v[204:207], s[2:3] offset:256
	s_waitcnt vmcnt(15)
; __device__ __forceinline__ float bf_lo(unsigned w) { return __uint_as_float(w << 16); }
; __device__ __forceinline__ float bf_hi(unsigned w) { return __uint_as_float(w & 0xffff0000u); }
; __device__ __forceinline__ unsigned cvt_pk_bf16(float lo, float hi) { unsigned r; asm volatile("v_cvt_pk_bf16_f32 %0, %1, %2" : "=v"(r) : "v"(lo), "v"(hi)); return r; }
;     __device__ __forceinline__ void operator()(const f32x4 (&acc)[2][2][4][2], const Unit& u, int wr, int wc, int fr, int fq) const {
;     ...
;                     if (ldp) { const u32x4 o = old8[m][bj];
;                         if (recip) { f[0] *= __builtin_amdgcn_rcpf(bf_lo(o.x)); f[1] *= __builtin_amdgcn_rcpf(bf_hi(o.x)); f[2] *= __builtin_amdgcn_rcpf(bf_lo(o.y)); f[3] *= __builtin_amdgcn_rcpf(bf_hi(o.y));
;                             f[4] *= __builtin_amdgcn_rcpf(bf_lo(o.z)); f[5] *= __builtin_amdgcn_rcpf(bf_hi(o.z)); f[6] *= __builtin_amdgcn_rcpf(bf_lo(o.w)); f[7] *= __builtin_amdgcn_rcpf(bf_hi(o.w)); }
;                         else { f[0] *= bf_lo(o.x); f[1] *= bf_hi(o.x); f[2] *= bf_lo(o.y); f[3] *= bf_hi(o.y); f[4] *= bf_lo(o.z); f[5] *= bf_hi(o.z); f[6] *= bf_lo(o.w); f[7] *= bf_hi(o.w); } }
;                     u32x4 w; w.x = cvt_pk_bf16(f[0], f[1]); w.y = cvt_pk_bf16(f[2], f[3]); w.z = cvt_pk_bf16(f[4], f[5]); w.w = cvt_pk_bf16(f[6], f[7]);
;                     if (st_lm) { if (recip) __builtin_nontemporal_store(w, (u32x4*)(stp + ((ai * 4 + m) * 2 + bj) * 512)); else *(u32x4*)(stp + ((ai * 4 + m) * 2 + bj) * 512) = w; }
;                     else *(u32x4*)(stp + (size_t)(row0 + ai * 128 + m * 16) * ld + col0 + bj * 128) = w; } }
	v_lshlrev_b32_e32 v244, 16, v208
	v_and_b32_e32 v245, s1, v208
	v_lshlrev_b32_e32 v246, 16, v209
	v_and_b32_e32 v247, s1, v209
	v_lshlrev_b32_e32 v248, 16, v210
	v_and_b32_e32 v249, s1, v210
	v_lshlrev_b32_e32 v250, 16, v211
	v_and_b32_e32 v251, s1, v211
	v_pk_mul_f32 v[68:69], v[68:69], v[244:245]
	v_pk_mul_f32 v[70:71], v[70:71], v[246:247]
	v_pk_mul_f32 v[64:65], v[64:65], v[248:249]
	v_pk_mul_f32 v[66:67], v[66:67], v[250:251]
	v_cvt_pk_bf16_f32 v208, v68, v69
	v_cvt_pk_bf16_f32 v209, v70, v71
	v_cvt_pk_bf16_f32 v210, v64, v65
	v_cvt_pk_bf16_f32 v211, v66, v67
	global_store_dwordx4 v168, v[208:211], s[2:3]
	s_waitcnt vmcnt(15)
	v_lshlrev_b32_e32 v244, 16, v212
	v_and_b32_e32 v245, s1, v212
	v_lshlrev_b32_e32 v246, 16, v213
	v_and_b32_e32 v247, s1, v213
	v_lshlrev_b32_e32 v248, 16, v214
	v_and_b32_e32 v249, s1, v214
	v_lshlrev_b32_e32 v250, 16, v215
	v_and_b32_e32 v251, s1, v215
	v_pk_mul_f32 v[56:57], v[56:57], v[244:245]
	v_pk_mul_f32 v[58:59], v[58:59], v[246:247]
	v_pk_mul_f32 v[52:53], v[52:53], v[248:249]
	v_pk_mul_f32 v[54:55], v[54:55], v[250:251]
	v_cvt_pk_bf16_f32 v212, v56, v57
	v_cvt_pk_bf16_f32 v213, v58, v59
	v_cvt_pk_bf16_f32 v214, v52, v53
	v_cvt_pk_bf16_f32 v215, v54, v55
	global_store_dwordx4 v168, v[212:215], s[2:3] offset:256
	s_waitcnt vmcnt(15)
	v_lshlrev_b32_e32 v244, 16, v216
	v_and_b32_e32 v245, s1, v216
	v_lshlrev_b32_e32 v246, 16, v217
	v_and_b32_e32 v247, s1, v217
	v_lshlrev_b32_e32 v248, 16, v218
	v_and_b32_e32 v249, s1, v218
	v_lshlrev_b32_e32 v250, 16, v219
	v_and_b32_e32 v251, s1, v219
	v_pk_mul_f32 v[44:45], v[44:45], v[244:245]
	v_pk_mul_f32 v[46:47], v[46:47], v[246:247]
	v_pk_mul_f32 v[40:41], v[40:41], v[248:249]
	v_pk_mul_f32 v[42:43], v[42:43], v[250:251]
	v_cvt_pk_bf16_f32 v216, v44, v45
	v_cvt_pk_bf16_f32 v217, v46, v47
	v_cvt_pk_bf16_f32 v218, v40, v41
	v_cvt_pk_bf16_f32 v219, v42, v43
	global_store_dwordx4 v169, v[216:219], s[2:3]
	s_waitcnt vmcnt(15)
	v_lshlrev_b32_e32 v244, 16, v220
	v_and_b32_e32 v245, s1, v220
	v_lshlrev_b32_e32 v246, 16, v221
	v_and_b32_e32 v247, s1, v221
	v_lshlrev_b32_e32 v248, 16, v222
	v_and_b32_e32 v249, s1, v222
	v_lshlrev_b32_e32 v250, 16, v223
	v_and_b32_e32 v251, s1, v223
	v_pk_mul_f32 v[36:37], v[36:37], v[244:245]
	v_pk_mul_f32 v[38:39], v[38:39], v[246:247]
	v_pk_mul_f32 v[32:33], v[32:33], v[248:249]
	v_pk_mul_f32 v[34:35], v[34:35], v[250:251]
	v_cvt_pk_bf16_f32 v220, v36, v37
	v_cvt_pk_bf16_f32 v221, v38, v39
	v_cvt_pk_bf16_f32 v222, v32, v33
	v_cvt_pk_bf16_f32 v223, v34, v35
	global_store_dwordx4 v169, v[220:223], s[2:3] offset:256
	s_waitcnt vmcnt(15)
	v_lshlrev_b32_e32 v244, 16, v228
	v_and_b32_e32 v245, s1, v228
	v_lshlrev_b32_e32 v246, 16, v229
	v_and_b32_e32 v247, s1, v229
	v_lshlrev_b32_e32 v248, 16, v230
	v_and_b32_e32 v249, s1, v230
	v_lshlrev_b32_e32 v250, 16, v231
	v_and_b32_e32 v251, s1, v231
	v_pk_mul_f32 v[28:29], v[28:29], v[244:245]
	v_pk_mul_f32 v[30:31], v[30:31], v[246:247]
	v_pk_mul_f32 v[24:25], v[24:25], v[248:249]
	v_pk_mul_f32 v[26:27], v[26:27], v[250:251]
	v_cvt_pk_bf16_f32 v228, v28, v29
	v_cvt_pk_bf16_f32 v229, v30, v31
	v_cvt_pk_bf16_f32 v230, v24, v25
	v_cvt_pk_bf16_f32 v231, v26, v27
	global_store_dwordx4 v170, v[228:231], s[2:3]
	s_waitcnt vmcnt(15)
	v_lshlrev_b32_e32 v244, 16, v232
	v_and_b32_e32 v245, s1, v232
	v_lshlrev_b32_e32 v246, 16, v233
	v_and_b32_e32 v247, s1, v233
	v_lshlrev_b32_e32 v248, 16, v234
	v_and_b32_e32 v249, s1, v234
	v_lshlrev_b32_e32 v250, 16, v235
	v_and_b32_e32 v251, s1, v235
	v_pk_mul_f32 v[20:21], v[20:21], v[244:245]
	v_pk_mul_f32 v[22:23], v[22:23], v[246:247]
	v_pk_mul_f32 v[16:17], v[16:17], v[248:249]
	v_pk_mul_f32 v[18:19], v[18:19], v[250:251]
	v_cvt_pk_bf16_f32 v232, v20, v21
	v_cvt_pk_bf16_f32 v233, v22, v23
	v_cvt_pk_bf16_f32 v234, v16, v17
	v_cvt_pk_bf16_f32 v235, v18, v19
	global_store_dwordx4 v170, v[232:235], s[2:3] offset:256
	s_waitcnt vmcnt(15)
	v_lshlrev_b32_e32 v244, 16, v236
	v_and_b32_e32 v245, s1, v236
	v_lshlrev_b32_e32 v246, 16, v237
	v_and_b32_e32 v247, s1, v237
	v_lshlrev_b32_e32 v248, 16, v238
	v_and_b32_e32 v249, s1, v238
	v_lshlrev_b32_e32 v250, 16, v239
	v_and_b32_e32 v251, s1, v239
	v_pk_mul_f32 v[12:13], v[12:13], v[244:245]
	v_pk_mul_f32 v[14:15], v[14:15], v[246:247]
	v_pk_mul_f32 v[8:9], v[8:9], v[248:249]
	v_pk_mul_f32 v[10:11], v[10:11], v[250:251]
	v_cvt_pk_bf16_f32 v236, v12, v13
	v_cvt_pk_bf16_f32 v237, v14, v15
	v_cvt_pk_bf16_f32 v238, v8, v9
	v_cvt_pk_bf16_f32 v239, v10, v11
	global_store_dwordx4 v171, v[236:239], s[2:3]
	s_waitcnt vmcnt(15)
	v_lshlrev_b32_e32 v244, 16, v240
	v_and_b32_e32 v245, s1, v240
	v_lshlrev_b32_e32 v246, 16, v241
	v_and_b32_e32 v247, s1, v241
	v_lshlrev_b32_e32 v248, 16, v242
	v_and_b32_e32 v249, s1, v242
	v_lshlrev_b32_e32 v250, 16, v243
	v_and_b32_e32 v251, s1, v243
	v_pk_mul_f32 v[4:5], v[4:5], v[244:245]
	v_pk_mul_f32 v[6:7], v[6:7], v[246:247]
	v_pk_mul_f32 v[0:1], v[0:1], v[248:249]
	v_pk_mul_f32 v[2:3], v[2:3], v[250:251]
	v_cvt_pk_bf16_f32 v240, v4, v5
	v_cvt_pk_bf16_f32 v241, v6, v7
	v_cvt_pk_bf16_f32 v242, v0, v1
	v_cvt_pk_bf16_f32 v243, v2, v3
	global_store_dwordx4 v171, v[240:243], s[2:3] offset:256
	s_waitcnt vmcnt(0)
	s_waitcnt vmcnt(0)
	s_cmpk_lt_u32 s10, 0x100
	s_cbranch_scc0 .LBB0_671
	s_barrier
